# instruction selection: 33 adjacent scalar f32 add/mul pairs in the attention bodies packed into v_pk ops
# speedup vs baseline: 1.0060x; 1.0004x over previous
; #define LAS __attribute__((address_space(3)))
; template <int MODE> ...
;     ...
;                     for (int ks = 0; ks < 2; ++ks) kf[jj][kt][ks] = *(const LAS bf16x8*)(Sl + kad[jj][ks] + (32 * hf + 16 * kt) * 128);
;             f32x4 bb[2][2];
; #pragma unroll
;             for (int jj = 0; jj < 2; ++jj) { const LAS f32x4* bl = bcp + ((MODE == 0) ? (dr0 + t - act0) * 8 : 16 * t + 8 * hf) + bofs[jj];
; #pragma unroll
;                 for (int kt = 0; kt < 2; ++kt) bb[jj][kt] = bl[4 * kt]; }
;             s16x4 vlo[2][4], vhi[2][4];
; #pragma unroll
;             for (int jj = 0; jj < 2; ++jj)
; #pragma unroll
;                 for (int dt = 0; dt < 4; ++dt) { const LAS unsigned char* vp = Sl + vad[jj] + (32 * hf) * 128 + ((dt ^ sv) << 5);
;                     vlo[jj][dt] = __builtin_bit_cast(s16x4, __builtin_amdgcn_ds_read_tr16_b64_v4i16((LAS s16x4*)(vp)));
;                     vhi[jj][dt] = __builtin_bit_cast(s16x4, __builtin_amdgcn_ds_read_tr16_b64_v4i16((LAS s16x4*)(vp + 2048))); }
;             __builtin_amdgcn_sched_barrier(0);
;             f32x4 s[2][2];
; #pragma unroll
;             for (int jj = 0; jj < 2; ++jj)
; #pragma unroll
;                 for (int kt = 0; kt < 2; ++kt) { f32x4 a = (MODE == 0) ? bb[jj][kt] + mneg[jj][kt] : bb[jj][kt];
;                     a = __builtin_amdgcn_mfma_f32_16x16x32_bf16(kf[jj][kt][0], qf[jj][0], a, 0, 0, 0);
;                     s[jj][kt] = __builtin_amdgcn_mfma_f32_16x16x32_bf16(kf[jj][kt][1], qf[jj][1], a, 0, 0, 0); }
;             u32x4 pw[2];
; #pragma unroll
;             for (int jj = 0; jj < 2; ++jj) {
;                 const float tm = vmax3(vmax3(s[jj][0][0], s[jj][0][1], s[jj][0][2]), vmax3(s[jj][0][3], s[jj][1][0], s[jj][1][1]), vmax3(s[jj][1][2], s[jj][1][3], s[jj][1][3]));
;                 const float mn = quad_max3(mrun[jj], tm);
;                 const float alpha = __builtin_amdgcn_exp2f(mrun[jj] - mn);
;                 mrun[jj] = mn;
;                 float rsum = 0.f;
; #pragma unroll
;                 for (int kt = 0; kt < 2; ++kt)
; #pragma unroll
;                     for (int e = 0; e < 4; ++e) { s[jj][kt][e] = __builtin_amdgcn_exp2f(s[jj][kt][e] - mn); rsum += s[jj][kt][e]; }
;                 lrun[jj] = lrun[jj] * alpha + rsum;
; #pragma unroll
;                 for (int dt = 0; dt < 4; ++dt) o[jj][dt] *= alpha;
.LBB0_278:
	s_sub_i32 s52, s25, s23
	v_lshlrev_b32_e32 v94, 5, v93
	s_add_i32 s0, s23, 7
	v_xor_b32_e32 v95, 32, v94
	v_xor_b32_e32 v96, 64, v94
	s_cmp_gt_u32 s0, 7
	v_xor_b32_e32 v97, 0x60, v94
	s_cbranch_scc1 .LBB0_291
	s_lshl_b32 s0, s86, 14
	s_add_i32 s0, s0, 0
	v_add_u32_e32 v0, s0, v89
	s_lshl_b32 s14, s52, 7
	v_add_u32_e32 v2, s0, v88
	ds_read_b128 v[6:9], v0
	ds_read_b128 v[10:13], v0 offset:2048
	ds_read_b128 v[14:17], v2
	ds_read_b128 v[34:37], v2 offset:2048
	v_add_u32_e32 v0, s0, v92
	s_add_i32 s14, s24, s14
	v_add_u32_e32 v2, s0, v91
	ds_read_b128 v[38:41], v0
	ds_read_b128 v[42:45], v0 offset:2048
	ds_read_b128 v[46:49], v2
	ds_read_b128 v[50:53], v2 offset:2048
	v_lshl_add_u32 v0, v87, 4, s14
	ds_read_b128 v[54:57], v0
	ds_read_b128 v[58:61], v0 offset:64
	v_lshl_add_u32 v0, v90, 4, s14
	ds_read_b128 v[62:65], v0
	ds_read_b128 v[66:69], v0 offset:64
	v_add3_u32 v0, v86, v122, s0
	v_add_u32_e32 v2, v0, v94
	v_add_u32_e32 v3, v0, v95
	ds_read_b64_tr_b16 v[70:71], v2 offset:8192
	ds_read_b64_tr_b16 v[72:73], v2 offset:10240
	ds_read_b64_tr_b16 v[74:75], v3 offset:8192
	ds_read_b64_tr_b16 v[76:77], v3 offset:10240
	v_add_u32_e32 v2, v0, v96
	v_add_u32_e32 v0, v0, v97
	ds_read_b64_tr_b16 v[78:79], v2 offset:8192
	ds_read_b64_tr_b16 v[80:81], v2 offset:10240
	ds_read_b64_tr_b16 v[126:127], v0 offset:8192
	ds_read_b64_tr_b16 v[128:129], v0 offset:10240
	v_add3_u32 v0, v123, v122, s0
	v_add_u32_e32 v2, v0, v94
	v_add_u32_e32 v3, v0, v95
	ds_read_b64_tr_b16 v[130:131], v2 offset:8192
	ds_read_b64_tr_b16 v[132:133], v2 offset:10240
	ds_read_b64_tr_b16 v[134:135], v3 offset:8192
	ds_read_b64_tr_b16 v[136:137], v3 offset:10240
	v_add_u32_e32 v2, v0, v96
	v_add_u32_e32 v0, v0, v97
	ds_read_b64_tr_b16 v[138:139], v2 offset:8192
	ds_read_b64_tr_b16 v[140:141], v2 offset:10240
	ds_read_b64_tr_b16 v[2:3], v0 offset:8192
	ds_read_b64_tr_b16 v[4:5], v0 offset:10240
	s_waitcnt lgkmcnt(14)
	v_pk_add_f32 v[56:57], v[112:113], v[56:57]
	v_pk_add_f32 v[54:55], v[110:111], v[54:55]
	s_mov_b32 s0, 0xf149f2ca
	s_nop 0
	v_mfma_f32_16x16x32_bf16 v[6:9], v[6:9], v[30:33], v[54:57]
	s_nop 2
	v_pk_add_f32 v[56:57], v[114:115], v[60:61]
	v_pk_add_f32 v[54:55], v[108:109], v[58:59]
	v_mfma_f32_16x16x32_bf16 v[6:9], v[14:17], v[26:29], v[6:9]
	v_pk_add_f32 v[16:17], v[106:107], v[64:65]
	v_pk_add_f32 v[14:15], v[102:103], v[62:63]
	v_mfma_f32_16x16x32_bf16 v[10:13], v[10:13], v[30:33], v[54:57]
	v_mfma_f32_16x16x32_bf16 v[10:13], v[34:37], v[26:29], v[10:13]
	s_nop 2
	v_maximum3_f32 v0, v6, v7, v8
	v_pk_add_f32 v[56:57], v[104:105], v[68:69]
	v_pk_add_f32 v[54:55], v[100:101], v[66:67]
	v_mfma_f32_16x16x32_bf16 v[14:17], v[38:41], v[22:25], v[14:17]
	v_mfma_f32_16x16x32_bf16 v[14:17], v[46:49], v[18:21], v[14:17]
	v_maximum3_f32 v34, v9, v10, v11
	v_maximum3_f32 v35, v12, v13, v13
	v_maximum3_f32 v0, v0, v34, v35
	v_mov_b32_e32 v34, v0
	s_nop 1
	v_permlane16_swap_b32_e32 v0, v34
	v_maximum3_f32 v0, v0, v34, v34
	v_mov_b32_e32 v34, v0
	s_nop 1
	v_permlane32_swap_b32_e32 v0, v34
	v_maximum3_f32 v125, v0, s0, v34
	v_mfma_f32_16x16x32_bf16 v[34:37], v[42:45], v[22:25], v[54:57]
	v_sub_f32_e32 v6, v6, v125
	v_exp_f32_e32 v38, v6
	v_sub_f32_e32 v6, v7, v125
	v_mfma_f32_16x16x32_bf16 v[34:37], v[50:53], v[18:21], v[34:37]
	v_exp_f32_e32 v40, v6
	v_sub_f32_e32 v6, v8, v125
	v_exp_f32_e32 v42, v6
	v_sub_f32_e32 v6, v9, v125
	v_sub_f32_e32 v0, 0xf149f2ca, v125
	v_exp_f32_e32 v66, v6
	v_sub_f32_e32 v6, v10, v125
	v_exp_f32_e32 v68, v6
	v_sub_f32_e32 v6, v11, v125
	v_exp_f32_e32 v146, v0
	v_maximum3_f32 v0, v14, v15, v16
	v_maximum3_f32 v10, v17, v34, v35
	v_maximum3_f32 v11, v36, v37, v37
	v_maximum3_f32 v0, v0, v10, v11
	v_mov_b32_e32 v10, v0
	s_nop 1
	v_permlane16_swap_b32_e32 v0, v10
	v_maximum3_f32 v0, v0, v10, v10
	v_mov_b32_e32 v10, v0
	s_nop 1
	v_permlane32_swap_b32_e32 v0, v10
	v_maximum3_f32 v124, v0, s0, v10
	v_exp_f32_e32 v98, v6
	v_sub_f32_e32 v6, v12, v125
	v_sub_f32_e32 v0, 0xf149f2ca, v124
	v_exp_f32_e32 v142, v6
	v_sub_f32_e32 v6, v13, v125
	v_sub_f32_e32 v10, v14, v124
	v_exp_f32_e32 v147, v0
	v_exp_f32_e32 v144, v6
	v_exp_f32_e32 v39, v10
	v_sub_f32_e32 v10, v15, v124
	v_exp_f32_e32 v41, v10
	v_sub_f32_e32 v10, v16, v124
	v_sub_f32_e32 v0, v34, v124
	v_exp_f32_e32 v43, v10
	v_sub_f32_e32 v10, v17, v124
	v_exp_f32_e32 v69, v0
	v_sub_f32_e32 v0, v35, v124
	v_exp_f32_e32 v67, v10
	v_pk_mul_f32 v[10:11], v[146:147], 0 op_sel_hi:[1,0]
	v_exp_f32_e32 v99, v0
	v_sub_f32_e32 v0, v36, v124
	v_cvt_pk_bf16_f32 v6, v38, v40
	v_cvt_pk_bf16_f32 v7, v42, v66
	v_cvt_pk_bf16_f32 v8, v68, v98
	v_cvt_pk_bf16_f32 v9, v142, v144
	v_mov_b32_e32 v14, v10
	v_mov_b32_e32 v15, v10
	v_mov_b32_e32 v16, v10
	v_mov_b32_e32 v17, v10
	v_exp_f32_e32 v143, v0
	v_sub_f32_e32 v0, v37, v124
	v_mfma_f32_16x16x32_bf16 v[54:57], v[70:73], v[6:9], v[14:17]
	v_exp_f32_e32 v145, v0
	v_mov_b32_e32 v10, v11
	v_mov_b32_e32 v12, v11
	s_waitcnt lgkmcnt(12)
	v_mfma_f32_16x16x32_bf16 v[62:65], v[74:77], v[6:9], v[14:17]
	v_mov_b32_e32 v13, v11
	v_cvt_pk_bf16_f32 v34, v39, v41
	v_cvt_pk_bf16_f32 v35, v43, v67
	s_waitcnt lgkmcnt(10)
	v_mfma_f32_16x16x32_bf16 v[58:61], v[78:81], v[6:9], v[14:17]
	v_cvt_pk_bf16_f32 v36, v69, v99
	v_cvt_pk_bf16_f32 v37, v143, v145
	s_waitcnt lgkmcnt(8)
	v_mfma_f32_16x16x32_bf16 v[50:53], v[126:129], v[6:9], v[14:17]
	v_add_f32_e64 v6, v38, 0
	v_add_f32_e64 v7, v39, 0
	v_pk_add_f32 v[6:7], v[40:41], v[6:7]
	s_waitcnt lgkmcnt(6)
	v_mfma_f32_16x16x32_bf16 v[46:49], v[130:133], v[34:37], v[10:13]
	v_pk_add_f32 v[6:7], v[42:43], v[6:7]
	v_pk_add_f32 v[6:7], v[66:67], v[6:7]
	s_waitcnt lgkmcnt(4)
	v_mfma_f32_16x16x32_bf16 v[42:45], v[134:137], v[34:37], v[10:13]
	v_pk_add_f32 v[6:7], v[68:69], v[6:7]
	v_pk_add_f32 v[6:7], v[98:99], v[6:7]
	s_waitcnt lgkmcnt(2)
	v_mfma_f32_16x16x32_bf16 v[38:41], v[138:141], v[34:37], v[10:13]
	v_pk_add_f32 v[6:7], v[142:143], v[6:7]
	v_pk_add_f32 v[6:7], v[144:145], v[6:7]
	s_waitcnt lgkmcnt(0)
	v_mfma_f32_16x16x32_bf16 v[34:37], v[2:5], v[34:37], v[10:13]
	v_fma_f32 v98, v146, 0, v6
	v_fma_f32 v99, v147, 0, v7
	s_cmp_eq_u32 s41, 1
	s_cbranch_scc1 .LBB0_281
	s_branch .LBB0_292

; #define LAS __attribute__((address_space(3)))
; #define GAS __attribute__((address_space(1)))
; template <int MODE> ...
;     ...
;                     for (int ks = 0; ks < 2; ++ks) kf[jj][kt][ks] = *(const LAS bf16x8*)(Sl + kad[jj][ks] + (32 * hf + 16 * kt) * 128);
;             f32x4 bb[2][2];
; #pragma unroll
;             for (int jj = 0; jj < 2; ++jj) { const LAS f32x4* bl = bcp + ((MODE == 0) ? (dr0 + t - act0) * 8 : 16 * t + 8 * hf) + bofs[jj];
; #pragma unroll
;                 for (int kt = 0; kt < 2; ++kt) bb[jj][kt] = bl[4 * kt]; }
;             s16x4 vlo[2][4], vhi[2][4];
; #pragma unroll
;             for (int jj = 0; jj < 2; ++jj)
; #pragma unroll
;                 for (int dt = 0; dt < 4; ++dt) { const LAS unsigned char* vp = Sl + vad[jj] + (32 * hf) * 128 + ((dt ^ sv) << 5);
;                     vlo[jj][dt] = __builtin_bit_cast(s16x4, __builtin_amdgcn_ds_read_tr16_b64_v4i16((LAS s16x4*)(vp)));
;                     vhi[jj][dt] = __builtin_bit_cast(s16x4, __builtin_amdgcn_ds_read_tr16_b64_v4i16((LAS s16x4*)(vp + 2048))); }
;     ...
;     head(nT - 1);
;     bf16x8 qn[2][2];
;     { const GAS bf16_t* qs = nQ ? (const GAS bf16_t*)nQ : (const GAS bf16_t*)proj + (size_t)qtok0 * NIN + qcol;
; #pragma unroll
;       for (int jj = 0; jj < 2; ++jj)
; #pragma unroll
;           for (int ks = 0; ks < 2; ++ks) qn[jj][ks] = *(const GAS bf16x8*)(qs + (size_t)(16 * jj) * NIN + 32 * ks + qoff); }
;     body(nT - 1);
.LBB0_283:
	s_add_i32 s42, s86, s26
	s_add_i32 s0, s42, 1
	s_mul_hi_i32 s14, s0, 0x55555556
	s_lshr_b32 s15, s14, 31
	s_add_i32 s14, s14, s15
	s_mul_i32 s14, s14, 3
	s_sub_i32 s0, s0, s14
	s_lshl_b32 s0, s0, 14
	s_add_i32 s0, s0, s94
	s_add_u32 s34, s34, 0x48000
	s_addc_u32 s35, s35, 0
	s_add_u32 s30, s30, 0x48000
	s_barrier
	s_addc_u32 s31, s31, 0
	s_mov_b32 m0, s0
	s_nop 0
	global_load_lds_dwordx4 v84, s[34:35]
	s_add_u32 m0, m0, 0x2000
	s_nop 0
	global_load_lds_dwordx4 v85, s[30:31]
	v_lshl_add_u64 v[6:7], v[82:83], 1, s[38:39]
	global_load_dwordx4 v[2:5], v[6:7], off
	global_load_dwordx4 v[10:13], v[6:7], off offset:64
	v_add_co_u32_e32 v6, vcc, 0x12000, v6
	s_cmp_gt_u32 s40, s27
	s_nop 0
	v_addc_co_u32_e32 v7, vcc, 0, v7, vcc
	global_load_dwordx4 v[14:17], v[6:7], off
	s_nop 0
	global_load_dwordx4 v[6:9], v[6:7], off offset:64
	s_cselect_b64 s[30:31], -1, 0
	s_add_i32 s0, s23, 8
	s_cmp_le_i32 s26, s0
	s_cselect_b64 s[26:27], -1, 0
	s_and_b64 s[26:27], s[30:31], s[26:27]
	s_and_b64 vcc, exec, s[26:27]
	s_cbranch_vccz .LBB0_285
	s_add_i32 s0, s41, s86
	s_mul_hi_i32 s14, s0, 0x55555556
	s_lshr_b32 s15, s14, 31
	s_add_i32 s14, s14, s15
	s_mul_i32 s14, s14, 3
	s_sub_i32 s0, s0, s14
	s_lshl_b32 s0, s0, 14
	s_sub_i32 s14, s41, s23
	s_add_i32 s0, s0, 0
	s_add_i32 s14, s14, s25
	v_add_u32_e32 v0, s0, v89
	s_lshl_b32 s14, s14, 7
	v_add_u32_e32 v66, s0, v88
	ds_read_b128 v[126:129], v0
	ds_read_b128 v[130:133], v0 offset:2048
	ds_read_b128 v[134:137], v66
	ds_read_b128 v[138:141], v66 offset:2048
	v_add_u32_e32 v0, s0, v92
	s_add_i32 s24, s24, s14
	v_add_u32_e32 v66, s0, v91
	ds_read_b128 v[142:145], v0
	ds_read_b128 v[146:149], v0 offset:2048
	ds_read_b128 v[150:153], v66
	ds_read_b128 v[154:157], v66 offset:2048
	v_lshl_add_u32 v0, v87, 4, s24
	ds_read_b128 v[158:161], v0
	ds_read_b128 v[162:165], v0 offset:64
	v_lshl_add_u32 v0, v90, 4, s24
	ds_read_b128 v[166:169], v0
	ds_read_b128 v[170:173], v0 offset:64
	v_lshlrev_b32_e32 v0, 5, v93
	v_add3_u32 v66, v86, v122, s0
	v_add_u32_e32 v67, v66, v0
	v_xor_b32_e32 v68, 32, v0
	v_add_u32_e32 v69, v66, v68
	ds_read_b64_tr_b16 v[94:95], v67 offset:8192
	ds_read_b64_tr_b16 v[96:97], v67 offset:10240
	ds_read_b64_tr_b16 v[90:91], v69 offset:8192
	ds_read_b64_tr_b16 v[92:93], v69 offset:10240
	v_xor_b32_e32 v67, 64, v0
	v_xor_b32_e32 v70, 0x60, v0
	v_add_u32_e32 v69, v66, v67
	v_add_u32_e32 v66, v66, v70
	ds_read_b64_tr_b16 v[86:87], v69 offset:8192
	ds_read_b64_tr_b16 v[88:89], v69 offset:10240
	ds_read_b64_tr_b16 v[82:83], v66 offset:8192
	ds_read_b64_tr_b16 v[84:85], v66 offset:10240
	v_add3_u32 v66, v123, v122, s0
	v_add_u32_e32 v0, v66, v0
	v_add_u32_e32 v68, v66, v68
	ds_read_b64_tr_b16 v[78:79], v0 offset:8192
	ds_read_b64_tr_b16 v[80:81], v0 offset:10240
	ds_read_b64_tr_b16 v[74:75], v68 offset:8192
	ds_read_b64_tr_b16 v[76:77], v68 offset:10240
	v_add_u32_e32 v0, v66, v67
	v_add_u32_e32 v68, v66, v70
	ds_read_b64_tr_b16 v[70:71], v0 offset:8192
	ds_read_b64_tr_b16 v[72:73], v0 offset:10240
	ds_read_b64_tr_b16 v[66:67], v68 offset:8192
	ds_read_b64_tr_b16 v[68:69], v68 offset:10240
	s_waitcnt lgkmcnt(14)
; __device__ __forceinline__ unsigned cvtpk(float lo, float hi) { f32x2 v = {lo, hi}; bf16x2_t b = __builtin_convertvector(v, bf16x2_t); return __builtin_bit_cast(unsigned, b); }
; __device__ __forceinline__ float vmax3(float a, float b, float c) { return __builtin_elementwise_maximum(__builtin_elementwise_maximum(a, b), c); }
; template <int MODE> ...
;     ...
;             f32x4 s[2][2];
; #pragma unroll
;             for (int jj = 0; jj < 2; ++jj)
; #pragma unroll
;                 for (int kt = 0; kt < 2; ++kt) { f32x4 a = (MODE == 0) ? bb[jj][kt] + mneg[jj][kt] : bb[jj][kt];
;                     a = __builtin_amdgcn_mfma_f32_16x16x32_bf16(kf[jj][kt][0], qf[jj][0], a, 0, 0, 0);
;                     s[jj][kt] = __builtin_amdgcn_mfma_f32_16x16x32_bf16(kf[jj][kt][1], qf[jj][1], a, 0, 0, 0); }
;             u32x4 pw[2];
; #pragma unroll
;             for (int jj = 0; jj < 2; ++jj) {
;                 const float tm = vmax3(vmax3(s[jj][0][0], s[jj][0][1], s[jj][0][2]), vmax3(s[jj][0][3], s[jj][1][0], s[jj][1][1]), vmax3(s[jj][1][2], s[jj][1][3], s[jj][1][3]));
;                 const float mn = quad_max3(mrun[jj], tm);
;                 const float alpha = __builtin_amdgcn_exp2f(mrun[jj] - mn);
;                 mrun[jj] = mn;
;                 float rsum = 0.f;
; #pragma unroll
;                 for (int kt = 0; kt < 2; ++kt)
; #pragma unroll
;                     for (int e = 0; e < 4; ++e) { s[jj][kt][e] = __builtin_amdgcn_exp2f(s[jj][kt][e] - mn); rsum += s[jj][kt][e]; }
;                 lrun[jj] = lrun[jj] * alpha + rsum;
; #pragma unroll
;                 for (int dt = 0; dt < 4; ++dt) o[jj][dt] *= alpha;
;                 pw[jj].x = cvtpk(s[jj][0][0], s[jj][0][1]); pw[jj].y = cvtpk(s[jj][0][2], s[jj][0][3]); pw[jj].z = cvtpk(s[jj][1][0], s[jj][1][1]); pw[jj].w = cvtpk(s[jj][1][2], s[jj][1][3]);
;             }
; #pragma unroll
;             for (int jj = 0; jj < 2; ++jj)
; #pragma unroll
;                 for (int dt = 0; dt < 4; ++dt) {
;                     const bf16x8 vf = (bf16x8){vlo[jj][dt][0], vlo[jj][dt][1], vlo[jj][dt][2], vlo[jj][dt][3], vhi[jj][dt][0], vhi[jj][dt][1], vhi[jj][dt][2], vhi[jj][dt][3]};
;                     o[jj][dt] = __builtin_amdgcn_mfma_f32_16x16x32_bf16(vf, __builtin_bit_cast(bf16x8, pw[jj]), o[jj][dt], 0, 0, 0); }
	v_pk_add_f32 v[112:113], v[112:113], v[160:161]
	v_pk_add_f32 v[110:111], v[110:111], v[158:159]
	v_pk_add_f32 v[114:115], v[114:115], v[164:165]
	v_pk_add_f32 v[100:101], v[100:101], v[170:171]
	v_mfma_f32_16x16x32_bf16 v[110:113], v[126:129], v[30:33], v[110:113]
	v_mfma_f32_16x16x32_bf16 v[126:129], v[134:137], v[26:29], v[110:113]
	s_nop 6
	v_pk_add_f32 v[112:113], v[108:109], v[162:163]
	v_maximum3_f32 v0, v126, v127, v128
	v_pk_add_f32 v[108:109], v[106:107], v[168:169]
	v_mfma_f32_16x16x32_bf16 v[30:33], v[130:133], v[30:33], v[112:115]
	v_pk_add_f32 v[106:107], v[102:103], v[166:167]
	v_pk_add_f32 v[102:103], v[104:105], v[172:173]
	v_mfma_f32_16x16x32_bf16 v[26:29], v[138:141], v[26:29], v[30:33]
	s_nop 7
	v_maximum3_f32 v30, v129, v26, v27
	v_maximum3_f32 v31, v28, v29, v29
	v_maximum3_f32 v0, v0, v30, v31
	v_mov_b32_e32 v104, v0
	s_nop 1
	v_permlane16_swap_b32_e32 v0, v104
	v_mfma_f32_16x16x32_bf16 v[30:33], v[142:145], v[22:25], v[106:109]
	v_maximum3_f32 v0, v0, v104, v104
	v_mov_b32_e32 v104, v0
	s_nop 1
	v_permlane32_swap_b32_e32 v0, v104
	v_mfma_f32_16x16x32_bf16 v[22:25], v[146:149], v[22:25], v[100:103]
	v_maximum3_f32 v0, v125, v0, v104
	v_mfma_f32_16x16x32_bf16 v[30:33], v[150:153], v[18:21], v[30:33]
	s_nop 0
	v_sub_f32_e32 v100, v125, v0
	v_exp_f32_e32 v122, v100
	v_sub_f32_e32 v101, v126, v0
	v_mfma_f32_16x16x32_bf16 v[18:21], v[154:157], v[18:21], v[22:25]
	v_exp_f32_e32 v104, v101
	v_pk_mul_f32 v[60:61], v[60:61], v[122:123] op_sel_hi:[1,0]
	v_pk_mul_f32 v[58:59], v[58:59], v[122:123] op_sel_hi:[1,0]
	v_sub_f32_e32 v22, v127, v0
	v_exp_f32_e32 v106, v22
	v_sub_f32_e32 v22, v128, v0
	v_exp_f32_e32 v108, v22
	v_sub_f32_e32 v22, v129, v0
	v_exp_f32_e32 v110, v22
	v_sub_f32_e32 v22, v26, v0
	v_exp_f32_e32 v112, v22
	v_sub_f32_e32 v22, v27, v0
	v_exp_f32_e32 v114, v22
	v_sub_f32_e32 v22, v28, v0
	v_sub_f32_e32 v0, v29, v0
	v_exp_f32_e32 v126, v22
	v_exp_f32_e32 v128, v0
	v_pk_mul_f32 v[22:23], v[54:55], v[122:123] op_sel_hi:[1,0]
	v_maximum3_f32 v0, v30, v31, v32
	v_maximum3_f32 v54, v33, v18, v19
	v_maximum3_f32 v55, v20, v21, v21
	v_maximum3_f32 v0, v0, v54, v55
	v_mov_b32_e32 v54, v0
	s_nop 1
	v_permlane16_swap_b32_e32 v0, v54
	v_maximum3_f32 v0, v0, v54, v54
	v_mov_b32_e32 v54, v0
	s_nop 1
	v_permlane32_swap_b32_e32 v0, v54
	v_maximum3_f32 v0, v124, v0, v54
	v_sub_f32_e32 v30, v30, v0
	v_exp_f32_e32 v105, v30
	v_sub_f32_e32 v30, v31, v0
	v_exp_f32_e32 v107, v30
	v_sub_f32_e32 v30, v32, v0
	v_sub_f32_e32 v18, v18, v0
	v_exp_f32_e32 v109, v30
	v_sub_f32_e32 v30, v33, v0
	v_exp_f32_e32 v113, v18
	v_sub_f32_e32 v18, v19, v0
	v_sub_f32_e32 v54, v124, v0
	v_exp_f32_e32 v111, v30
	v_exp_f32_e32 v115, v18
	v_sub_f32_e32 v18, v20, v0
	v_pk_mul_f32 v[24:25], v[56:57], v[122:123] op_sel_hi:[1,0]
	v_pk_mul_f32 v[28:29], v[64:65], v[122:123] op_sel_hi:[1,0]
	v_pk_mul_f32 v[26:27], v[62:63], v[122:123] op_sel_hi:[1,0]
	v_pk_mul_f32 v[52:53], v[52:53], v[122:123] op_sel_hi:[1,0]
	v_pk_mul_f32 v[50:51], v[50:51], v[122:123] op_sel_hi:[1,0]
	v_exp_f32_e32 v127, v18
	v_sub_f32_e32 v0, v21, v0
	v_exp_f32_e32 v123, v54
	v_pk_add_f32 v[18:19], v[104:105], 0 op_sel_hi:[1,0]
	v_exp_f32_e32 v129, v0
	v_pk_add_f32 v[18:19], v[106:107], v[18:19]
	v_cvt_pk_bf16_f32 v100, v104, v106
	v_pk_add_f32 v[18:19], v[108:109], v[18:19]
	v_cvt_pk_bf16_f32 v101, v108, v110
	v_pk_add_f32 v[18:19], v[110:111], v[18:19]
	v_cvt_pk_bf16_f32 v102, v112, v114
	v_cvt_pk_bf16_f32 v103, v126, v128
	v_pk_add_f32 v[18:19], v[112:113], v[18:19]
	v_mov_b32_e32 v0, v123
	v_mfma_f32_16x16x32_bf16 v[54:57], v[94:97], v[100:103], v[22:25]
	v_pk_mul_f32 v[20:21], v[48:49], v[0:1] op_sel_hi:[1,0]
	s_waitcnt lgkmcnt(12)
	v_mfma_f32_16x16x32_bf16 v[62:65], v[90:93], v[100:103], v[26:29]
	v_cvt_pk_bf16_f32 v22, v105, v107
	v_cvt_pk_bf16_f32 v23, v109, v111
	v_cvt_pk_bf16_f32 v24, v113, v115
	v_pk_add_f32 v[26:27], v[114:115], v[18:19]
	v_pk_mul_f32 v[18:19], v[46:47], v[0:1] op_sel_hi:[1,0]
	v_cvt_pk_bf16_f32 v25, v127, v129
	s_waitcnt lgkmcnt(10)
	v_mfma_f32_16x16x32_bf16 v[58:61], v[86:89], v[100:103], v[58:61]
	v_pk_add_f32 v[26:27], v[126:127], v[26:27]
	v_pk_add_f32 v[26:27], v[128:129], v[26:27]
	s_waitcnt lgkmcnt(6)
	v_mfma_f32_16x16x32_bf16 v[46:49], v[78:81], v[22:25], v[18:21]
	v_fma_f32 v98, v98, v122, v26
	v_fma_f32 v99, v99, v123, v27
	s_nop 0
	v_pk_mul_f32 v[20:21], v[44:45], v[0:1] op_sel_hi:[1,0]
	v_pk_mul_f32 v[18:19], v[42:43], v[0:1] op_sel_hi:[1,0]
	v_mfma_f32_16x16x32_bf16 v[50:53], v[82:85], v[100:103], v[50:53]
	s_waitcnt lgkmcnt(4)
	v_mfma_f32_16x16x32_bf16 v[42:45], v[74:77], v[22:25], v[18:21]
	s_nop 2
	v_pk_mul_f32 v[20:21], v[40:41], v[0:1] op_sel_hi:[1,0]
	v_pk_mul_f32 v[18:19], v[38:39], v[0:1] op_sel_hi:[1,0]
	s_waitcnt lgkmcnt(2)
	s_nop 0
	v_mfma_f32_16x16x32_bf16 v[38:41], v[70:73], v[22:25], v[18:21]
	s_nop 2
	v_pk_mul_f32 v[20:21], v[36:37], v[0:1] op_sel_hi:[1,0]
	v_pk_mul_f32 v[18:19], v[34:35], v[0:1] op_sel_hi:[1,0]
	s_waitcnt lgkmcnt(0)
	s_nop 0
	v_mfma_f32_16x16x32_bf16 v[34:37], v[66:69], v[22:25], v[18:21]

; #define LAS __attribute__((address_space(3)))
; template <int MODE> ...
;     ...
;                     for (int ks = 0; ks < 2; ++ks) kf[jj][kt][ks] = *(const LAS bf16x8*)(Sl + kad[jj][ks] + (32 * hf + 16 * kt) * 128);
;             f32x4 bb[2][2];
; #pragma unroll
;             for (int jj = 0; jj < 2; ++jj) { const LAS f32x4* bl = bcp + ((MODE == 0) ? (dr0 + t - act0) * 8 : 16 * t + 8 * hf) + bofs[jj];
; #pragma unroll
;                 for (int kt = 0; kt < 2; ++kt) bb[jj][kt] = bl[4 * kt]; }
;             s16x4 vlo[2][4], vhi[2][4];
; #pragma unroll
;             for (int jj = 0; jj < 2; ++jj)
; #pragma unroll
;                 for (int dt = 0; dt < 4; ++dt) { const LAS unsigned char* vp = Sl + vad[jj] + (32 * hf) * 128 + ((dt ^ sv) << 5);
;                     vlo[jj][dt] = __builtin_bit_cast(s16x4, __builtin_amdgcn_ds_read_tr16_b64_v4i16((LAS s16x4*)(vp)));
;                     vhi[jj][dt] = __builtin_bit_cast(s16x4, __builtin_amdgcn_ds_read_tr16_b64_v4i16((LAS s16x4*)(vp + 2048))); }
;             __builtin_amdgcn_sched_barrier(0);
;             f32x4 s[2][2];
; #pragma unroll
;             for (int jj = 0; jj < 2; ++jj)
; #pragma unroll
;                 for (int kt = 0; kt < 2; ++kt) { f32x4 a = (MODE == 0) ? bb[jj][kt] + mneg[jj][kt] : bb[jj][kt];
;                     a = __builtin_amdgcn_mfma_f32_16x16x32_bf16(kf[jj][kt][0], qf[jj][0], a, 0, 0, 0);
;                     s[jj][kt] = __builtin_amdgcn_mfma_f32_16x16x32_bf16(kf[jj][kt][1], qf[jj][1], a, 0, 0, 0); }
;             u32x4 pw[2];
; #pragma unroll
;             for (int jj = 0; jj < 2; ++jj) {
;                 const float tm = vmax3(vmax3(s[jj][0][0], s[jj][0][1], s[jj][0][2]), vmax3(s[jj][0][3], s[jj][1][0], s[jj][1][1]), vmax3(s[jj][1][2], s[jj][1][3], s[jj][1][3]));
;                 const float mn = quad_max3(mrun[jj], tm);
;                 const float alpha = __builtin_amdgcn_exp2f(mrun[jj] - mn);
;                 mrun[jj] = mn;
;                 float rsum = 0.f;
; #pragma unroll
;                 for (int kt = 0; kt < 2; ++kt)
; #pragma unroll
;                     for (int e = 0; e < 4; ++e) { s[jj][kt][e] = __builtin_amdgcn_exp2f(s[jj][kt][e] - mn); rsum += s[jj][kt][e]; }
;                 lrun[jj] = lrun[jj] * alpha + rsum;
; #pragma unroll
;                 for (int dt = 0; dt < 4; ++dt) o[jj][dt] *= alpha;
.LBB0_298:
	s_add_i32 s0, s86, 1
	s_mul_hi_i32 s14, s0, 0x55555556
	s_lshr_b32 s15, s14, 31
	s_add_i32 s14, s14, s15
	s_mul_i32 s14, s14, 3
	s_sub_i32 s0, s0, s14
	s_lshl_b32 s0, s0, 14
	s_add_i32 s0, s0, 0
	v_add_u32_e32 v0, s0, v89
	s_lshl_b32 s14, s52, 7
	v_add_u32_e32 v2, s0, v88
	ds_read_b128 v[126:129], v0
	ds_read_b128 v[130:133], v0 offset:2048
	ds_read_b128 v[134:137], v2
	ds_read_b128 v[138:141], v2 offset:2048
	v_add_u32_e32 v0, s0, v92
	s_add_i32 s14, s24, s14
	v_add_u32_e32 v2, s0, v91
	ds_read_b128 v[142:145], v0
	ds_read_b128 v[146:149], v0 offset:2048
	ds_read_b128 v[150:153], v2
	ds_read_b128 v[154:157], v2 offset:2048
	v_lshl_add_u32 v0, v87, 4, s14
	ds_read_b128 v[158:161], v0 offset:128
	ds_read_b128 v[162:165], v0 offset:192
	v_lshl_add_u32 v0, v90, 4, s14
	ds_read_b128 v[166:169], v0 offset:128
	ds_read_b128 v[170:173], v0 offset:192
	v_add3_u32 v0, v86, v122, s0
	v_add_u32_e32 v2, v0, v94
	v_add_u32_e32 v3, v0, v95
	ds_read_b64_tr_b16 v[78:79], v2 offset:8192
	ds_read_b64_tr_b16 v[80:81], v2 offset:10240
	ds_read_b64_tr_b16 v[74:75], v3 offset:8192
	ds_read_b64_tr_b16 v[76:77], v3 offset:10240
	v_add_u32_e32 v2, v0, v96
	v_add_u32_e32 v0, v0, v97
	ds_read_b64_tr_b16 v[70:71], v2 offset:8192
	ds_read_b64_tr_b16 v[72:73], v2 offset:10240
	ds_read_b64_tr_b16 v[66:67], v0 offset:8192
	ds_read_b64_tr_b16 v[68:69], v0 offset:10240
	v_add3_u32 v0, v123, v122, s0
	v_add_u32_e32 v2, v0, v94
	v_add_u32_e32 v3, v0, v95
	ds_read_b64_tr_b16 v[14:15], v2 offset:8192
	ds_read_b64_tr_b16 v[16:17], v2 offset:10240
	ds_read_b64_tr_b16 v[10:11], v3 offset:8192
	ds_read_b64_tr_b16 v[12:13], v3 offset:10240
	v_add_u32_e32 v2, v0, v96
	v_add_u32_e32 v0, v0, v97
	ds_read_b64_tr_b16 v[6:7], v2 offset:8192
	ds_read_b64_tr_b16 v[8:9], v2 offset:10240
	ds_read_b64_tr_b16 v[2:3], v0 offset:8192
	ds_read_b64_tr_b16 v[4:5], v0 offset:10240
	s_waitcnt lgkmcnt(14)
	v_pk_add_f32 v[160:161], v[112:113], v[160:161]
	v_pk_add_f32 v[158:159], v[110:111], v[158:159]
	s_nop 1
	v_mfma_f32_16x16x32_bf16 v[126:129], v[126:129], v[30:33], v[158:161]
	s_nop 2
	v_pk_add_f32 v[160:161], v[114:115], v[164:165]
	v_pk_add_f32 v[158:159], v[108:109], v[162:163]
	v_mfma_f32_16x16x32_bf16 v[126:129], v[134:137], v[26:29], v[126:129]
	v_pk_add_f32 v[136:137], v[106:107], v[168:169]
	v_pk_add_f32 v[134:135], v[102:103], v[166:167]
	v_mfma_f32_16x16x32_bf16 v[130:133], v[130:133], v[30:33], v[158:161]
	v_mfma_f32_16x16x32_bf16 v[130:133], v[138:141], v[26:29], v[130:133]
	s_nop 2
	v_maximum3_f32 v0, v126, v127, v128
	v_pk_add_f32 v[160:161], v[104:105], v[172:173]
	v_pk_add_f32 v[158:159], v[100:101], v[170:171]
	v_mfma_f32_16x16x32_bf16 v[134:137], v[142:145], v[22:25], v[134:137]
	v_mfma_f32_16x16x32_bf16 v[134:137], v[150:153], v[18:21], v[134:137]
	v_maximum3_f32 v138, v129, v130, v131
	v_maximum3_f32 v139, v132, v133, v133
	v_maximum3_f32 v0, v0, v138, v139
	v_mov_b32_e32 v138, v0
	s_nop 1
	v_permlane16_swap_b32_e32 v0, v138
	v_maximum3_f32 v0, v0, v138, v138
	v_mov_b32_e32 v138, v0
	s_nop 1
	v_permlane32_swap_b32_e32 v0, v138
	v_maximum3_f32 v162, v125, v0, v138
	v_mfma_f32_16x16x32_bf16 v[138:141], v[146:149], v[22:25], v[158:161]
	v_sub_f32_e32 v0, v125, v162
	v_sub_f32_e32 v125, v126, v162
	v_exp_f32_e32 v142, v125
	v_sub_f32_e32 v125, v127, v162
	v_exp_f32_e32 v144, v125
	v_sub_f32_e32 v125, v128, v162
	v_mfma_f32_16x16x32_bf16 v[138:141], v[154:157], v[18:21], v[138:141]
	v_exp_f32_e32 v146, v125
	v_sub_f32_e32 v125, v129, v162
	v_exp_f32_e32 v148, v125
	v_sub_f32_e32 v125, v130, v162
	v_exp_f32_e32 v130, v125
	v_sub_f32_e32 v125, v131, v162
	v_exp_f32_e32 v150, v125
	v_sub_f32_e32 v125, v132, v162
	v_exp_f32_e32 v132, v0
	v_sub_f32_e32 v0, v133, v162
	v_exp_f32_e32 v152, v125
	v_exp_f32_e32 v154, v0
	v_maximum3_f32 v0, v134, v135, v136
	v_maximum3_f32 v125, v137, v138, v139
	v_maximum3_f32 v129, v140, v141, v141
	v_maximum3_f32 v0, v0, v125, v129
	v_mov_b32_e32 v125, v0
	s_nop 1
	v_permlane16_swap_b32_e32 v0, v125
	v_maximum3_f32 v0, v0, v125, v125
	v_mov_b32_e32 v125, v0
	s_nop 1
	v_permlane32_swap_b32_e32 v0, v125
	v_maximum3_f32 v156, v124, v0, v125
	v_pk_mul_f32 v[56:57], v[56:57], v[132:133] op_sel_hi:[1,0]
	v_pk_mul_f32 v[54:55], v[54:55], v[132:133] op_sel_hi:[1,0]
	v_pk_mul_f32 v[64:65], v[64:65], v[132:133] op_sel_hi:[1,0]
	v_pk_mul_f32 v[62:63], v[62:63], v[132:133] op_sel_hi:[1,0]
	v_pk_mul_f32 v[60:61], v[60:61], v[132:133] op_sel_hi:[1,0]
	v_pk_mul_f32 v[58:59], v[58:59], v[132:133] op_sel_hi:[1,0]
	v_pk_mul_f32 v[52:53], v[52:53], v[132:133] op_sel_hi:[1,0]
	v_pk_mul_f32 v[50:51], v[50:51], v[132:133] op_sel_hi:[1,0]
	v_sub_f32_e32 v0, v134, v156
	v_sub_f32_e32 v133, v139, v156
	v_exp_f32_e32 v143, v0
	v_sub_f32_e32 v0, v135, v156
	v_sub_f32_e32 v131, v136, v156
	v_exp_f32_e32 v151, v133
	v_sub_f32_e32 v133, v140, v156
	v_exp_f32_e32 v145, v0
	v_sub_f32_e32 v0, v124, v156
	v_exp_f32_e32 v147, v131
	v_sub_f32_e32 v131, v137, v156
	v_exp_f32_e32 v153, v133
	v_sub_f32_e32 v133, v141, v156
	v_exp_f32_e32 v149, v131
	v_sub_f32_e32 v131, v138, v156
	v_exp_f32_e32 v155, v133
	v_exp_f32_e32 v133, v0
	v_exp_f32_e32 v131, v131
	v_cvt_pk_bf16_f32 v126, v142, v144
	v_cvt_pk_bf16_f32 v127, v146, v148
	v_cvt_pk_bf16_f32 v128, v130, v150
	v_cvt_pk_bf16_f32 v129, v152, v154
	v_pk_add_f32 v[124:125], v[142:143], 0 op_sel_hi:[1,0]
	v_mov_b32_e32 v0, v133
	v_pk_add_f32 v[124:125], v[144:145], v[124:125]
	s_waitcnt lgkmcnt(10)
	v_mfma_f32_16x16x32_bf16 v[58:61], v[70:73], v[126:129], v[58:61]
	v_pk_mul_f32 v[48:49], v[48:49], v[0:1] op_sel_hi:[1,0]
	v_pk_mul_f32 v[46:47], v[46:47], v[0:1] op_sel_hi:[1,0]
	v_cvt_pk_bf16_f32 v70, v143, v145
	v_cvt_pk_bf16_f32 v71, v147, v149
	v_cvt_pk_bf16_f32 v72, v131, v151
	v_cvt_pk_bf16_f32 v73, v153, v155
	v_mfma_f32_16x16x32_bf16 v[54:57], v[78:81], v[126:129], v[54:57]
	v_pk_add_f32 v[78:79], v[146:147], v[124:125]
	v_pk_add_f32 v[78:79], v[148:149], v[78:79]
	s_waitcnt lgkmcnt(6)
	v_mfma_f32_16x16x32_bf16 v[46:49], v[14:17], v[70:73], v[46:49]
	v_pk_mul_f32 v[16:17], v[44:45], v[0:1] op_sel_hi:[1,0]
	v_pk_mul_f32 v[14:15], v[42:43], v[0:1] op_sel_hi:[1,0]
	v_mfma_f32_16x16x32_bf16 v[62:65], v[74:77], v[126:129], v[62:65]
	v_pk_add_f32 v[74:75], v[130:131], v[78:79]
	v_pk_add_f32 v[74:75], v[150:151], v[74:75]
	s_waitcnt lgkmcnt(4)
	v_mfma_f32_16x16x32_bf16 v[42:45], v[10:13], v[70:73], v[14:17]
	v_pk_mul_f32 v[12:13], v[40:41], v[0:1] op_sel_hi:[1,0]
	v_pk_mul_f32 v[10:11], v[38:39], v[0:1] op_sel_hi:[1,0]
	v_mfma_f32_16x16x32_bf16 v[50:53], v[66:69], v[126:129], v[50:53]
	v_pk_add_f32 v[66:67], v[152:153], v[74:75]
	v_pk_add_f32 v[14:15], v[154:155], v[66:67]
	s_waitcnt lgkmcnt(2)
	v_mfma_f32_16x16x32_bf16 v[38:41], v[6:9], v[70:73], v[10:13]
	v_pk_mul_f32 v[8:9], v[36:37], v[0:1] op_sel_hi:[1,0]
	v_pk_mul_f32 v[6:7], v[34:35], v[0:1] op_sel_hi:[1,0]
	v_pk_fma_f32 v[98:99], v[98:99], v[132:133], v[14:15]
	s_waitcnt lgkmcnt(0)
	v_mfma_f32_16x16x32_bf16 v[34:37], v[2:5], v[70:73], v[6:9]
	v_mov_b32_e32 v125, v162
	v_mov_b32_e32 v124, v156
	s_cmp_eq_u32 s41, 2
	s_cbranch_scc1 .LBB0_281

; #define LAS __attribute__((address_space(3)))
; template <int MODE> ...
;     ...
;         if (t >= act0 && t < act0 + actn) {
;         const LAS unsigned char* Sl = ring + ((t + base) % 3) * SLOT;
; #pragma unroll
;         for (int hf = 0; hf < NH; ++hf) {
;             if (MODE == 1) { const int ks = ktok0 + 64 * t + 32 * hf;
;                 if (ks + 31 < qtok0 - 128 || ks > qtok0 + 31 + 128) continue; }
;             bf16x8 kf[2][2][2];
; #pragma unroll
;             for (int jj = 0; jj < 2; ++jj)
; #pragma unroll
;                 for (int kt = 0; kt < 2; ++kt)
; #pragma unroll
;                     for (int ks = 0; ks < 2; ++ks) kf[jj][kt][ks] = *(const LAS bf16x8*)(Sl + kad[jj][ks] + (32 * hf + 16 * kt) * 128);
;             f32x4 bb[2][2];
; #pragma unroll
;             for (int jj = 0; jj < 2; ++jj) { const LAS f32x4* bl = bcp + ((MODE == 0) ? (dr0 + t - act0) * 8 : 16 * t + 8 * hf) + bofs[jj];
; #pragma unroll
;                 for (int kt = 0; kt < 2; ++kt) bb[jj][kt] = bl[4 * kt]; }
;             s16x4 vlo[2][4], vhi[2][4];
; #pragma unroll
;             for (int jj = 0; jj < 2; ++jj)
; #pragma unroll
;                 for (int dt = 0; dt < 4; ++dt) { const LAS unsigned char* vp = Sl + vad[jj] + (32 * hf) * 128 + ((dt ^ sv) << 5);
;                     vlo[jj][dt] = __builtin_bit_cast(s16x4, __builtin_amdgcn_ds_read_tr16_b64_v4i16((LAS s16x4*)(vp)));
;                     vhi[jj][dt] = __builtin_bit_cast(s16x4, __builtin_amdgcn_ds_read_tr16_b64_v4i16((LAS s16x4*)(vp + 2048))); }
.LBB0_305:
	s_add_i32 s0, s65, 2
	s_cmp_ge_i32 s0, s23
	s_cselect_b64 s[60:61], -1, 0
	s_cmp_lt_i32 s0, s45
	s_cselect_b64 s[66:67], -1, 0
	s_and_b64 s[60:61], s[60:61], s[66:67]
	s_andn2_b64 vcc, exec, s[60:61]
	s_cbranch_vccnz .LBB0_300
	s_add_i32 s0, s86, s65
	s_add_i32 s0, s0, 2
	s_mul_hi_i32 s14, s0, 0x55555556
	s_lshr_b32 s15, s14, 31
	s_add_i32 s14, s14, s15
	s_mul_i32 s14, s14, 3
	s_sub_i32 s0, s0, s14
	s_lshl_b32 s0, s0, 14
	s_add_i32 s0, s0, 0
	v_add_u32_e32 v2, s0, v89
	v_add_u32_e32 v3, s0, v88
	ds_read_b128 v[130:133], v2
	ds_read_b128 v[134:137], v2 offset:2048
	ds_read_b128 v[138:141], v3
	ds_read_b128 v[142:145], v3 offset:2048
	v_add_u32_e32 v2, s0, v92
	v_add_u32_e32 v3, s0, v91
	ds_read_b128 v[146:149], v2
	ds_read_b128 v[150:153], v2 offset:2048
	ds_read_b128 v[154:157], v3
	ds_read_b128 v[158:161], v3 offset:2048
	v_add_u32_e32 v2, s50, v128
	v_add_u32_e32 v3, 0x10480, v2
	v_add_u32_e32 v2, 0x104c0, v2
	ds_read_b128 v[162:165], v3
	ds_read_b128 v[166:169], v2
	v_add_u32_e32 v2, s50, v127
	v_add_u32_e32 v3, 0x10480, v2
	v_add_u32_e32 v2, 0x104c0, v2
	ds_read_b128 v[170:173], v3
	ds_read_b128 v[174:177], v2
	v_add_u32_e32 v2, s0, v0
	v_add_u32_e32 v3, v2, v94
	v_add_u32_e32 v4, v2, v95
	ds_read_b64_tr_b16 v[78:79], v3 offset:8192
	ds_read_b64_tr_b16 v[80:81], v3 offset:10240
	ds_read_b64_tr_b16 v[74:75], v4 offset:8192
	ds_read_b64_tr_b16 v[76:77], v4 offset:10240
	v_add_u32_e32 v3, v2, v96
	v_add_u32_e32 v2, v2, v97
	ds_read_b64_tr_b16 v[70:71], v3 offset:8192
	ds_read_b64_tr_b16 v[72:73], v3 offset:10240
	ds_read_b64_tr_b16 v[66:67], v2 offset:8192
	ds_read_b64_tr_b16 v[68:69], v2 offset:10240
	v_add_u32_e32 v2, s0, v126
	v_add_u32_e32 v3, v2, v94
	v_add_u32_e32 v4, v2, v95
	ds_read_b64_tr_b16 v[14:15], v3 offset:8192
	ds_read_b64_tr_b16 v[16:17], v3 offset:10240
	ds_read_b64_tr_b16 v[10:11], v4 offset:8192
	ds_read_b64_tr_b16 v[12:13], v4 offset:10240
	v_add_u32_e32 v3, v2, v96
	v_add_u32_e32 v4, v2, v97
	ds_read_b64_tr_b16 v[6:7], v3 offset:8192
	ds_read_b64_tr_b16 v[8:9], v3 offset:10240
	ds_read_b64_tr_b16 v[2:3], v4 offset:8192
	ds_read_b64_tr_b16 v[4:5], v4 offset:10240
	s_waitcnt lgkmcnt(14)
; __device__ __forceinline__ unsigned cvtpk(float lo, float hi) { f32x2 v = {lo, hi}; bf16x2_t b = __builtin_convertvector(v, bf16x2_t); return __builtin_bit_cast(unsigned, b); }
; __device__ __forceinline__ float vmax3(float a, float b, float c) { return __builtin_elementwise_maximum(__builtin_elementwise_maximum(a, b), c); }
; template <int MODE> ...
;     ...
;             f32x4 s[2][2];
; #pragma unroll
;             for (int jj = 0; jj < 2; ++jj)
; #pragma unroll
;                 for (int kt = 0; kt < 2; ++kt) { f32x4 a = (MODE == 0) ? bb[jj][kt] + mneg[jj][kt] : bb[jj][kt];
;                     a = __builtin_amdgcn_mfma_f32_16x16x32_bf16(kf[jj][kt][0], qf[jj][0], a, 0, 0, 0);
;                     s[jj][kt] = __builtin_amdgcn_mfma_f32_16x16x32_bf16(kf[jj][kt][1], qf[jj][1], a, 0, 0, 0); }
;             u32x4 pw[2];
; #pragma unroll
;             for (int jj = 0; jj < 2; ++jj) {
;                 const float tm = vmax3(vmax3(s[jj][0][0], s[jj][0][1], s[jj][0][2]), vmax3(s[jj][0][3], s[jj][1][0], s[jj][1][1]), vmax3(s[jj][1][2], s[jj][1][3], s[jj][1][3]));
;                 const float mn = quad_max3(mrun[jj], tm);
;                 const float alpha = __builtin_amdgcn_exp2f(mrun[jj] - mn);
;                 mrun[jj] = mn;
;                 float rsum = 0.f;
; #pragma unroll
;                 for (int kt = 0; kt < 2; ++kt)
; #pragma unroll
;                     for (int e = 0; e < 4; ++e) { s[jj][kt][e] = __builtin_amdgcn_exp2f(s[jj][kt][e] - mn); rsum += s[jj][kt][e]; }
;                 lrun[jj] = lrun[jj] * alpha + rsum;
; #pragma unroll
;                 for (int dt = 0; dt < 4; ++dt) o[jj][dt] *= alpha;
;                 pw[jj].x = cvtpk(s[jj][0][0], s[jj][0][1]); pw[jj].y = cvtpk(s[jj][0][2], s[jj][0][3]); pw[jj].z = cvtpk(s[jj][1][0], s[jj][1][1]); pw[jj].w = cvtpk(s[jj][1][2], s[jj][1][3]);
;             }
; #pragma unroll
;             for (int jj = 0; jj < 2; ++jj)
; #pragma unroll
;                 for (int dt = 0; dt < 4; ++dt) {
;                     const bf16x8 vf = (bf16x8){vlo[jj][dt][0], vlo[jj][dt][1], vlo[jj][dt][2], vlo[jj][dt][3], vhi[jj][dt][0], vhi[jj][dt][1], vhi[jj][dt][2], vhi[jj][dt][3]};
;                     o[jj][dt] = __builtin_amdgcn_mfma_f32_16x16x32_bf16(vf, __builtin_bit_cast(bf16x8, pw[jj]), o[jj][dt], 0, 0, 0); }
	v_pk_add_f32 v[164:165], v[112:113], v[164:165]
	v_pk_add_f32 v[162:163], v[110:111], v[162:163]
	s_nop 1
	v_mfma_f32_16x16x32_bf16 v[130:133], v[130:133], v[30:33], v[162:165]
	s_nop 2
	v_pk_add_f32 v[164:165], v[114:115], v[168:169]
	v_pk_add_f32 v[162:163], v[108:109], v[166:167]
	v_mfma_f32_16x16x32_bf16 v[130:133], v[138:141], v[26:29], v[130:133]
	v_pk_add_f32 v[140:141], v[106:107], v[172:173]
	v_pk_add_f32 v[138:139], v[102:103], v[170:171]
	v_mfma_f32_16x16x32_bf16 v[134:137], v[134:137], v[30:33], v[162:165]
	v_mfma_f32_16x16x32_bf16 v[134:137], v[142:145], v[26:29], v[134:137]
	s_nop 2
	v_maximum3_f32 v129, v130, v131, v132
	v_pk_add_f32 v[164:165], v[104:105], v[176:177]
	v_pk_add_f32 v[162:163], v[100:101], v[174:175]
	v_mfma_f32_16x16x32_bf16 v[138:141], v[146:149], v[22:25], v[138:141]
	v_mfma_f32_16x16x32_bf16 v[138:141], v[154:157], v[18:21], v[138:141]
	v_maximum3_f32 v142, v133, v134, v135
	v_maximum3_f32 v143, v136, v137, v137
	v_maximum3_f32 v129, v129, v142, v143
	v_mov_b32_e32 v142, v129
	s_nop 1
	v_permlane16_swap_b32_e32 v129, v142
	v_maximum3_f32 v129, v129, v142, v142
	v_mov_b32_e32 v142, v129
	s_nop 1
	v_permlane32_swap_b32_e32 v129, v142
	v_maximum3_f32 v129, v125, v129, v142
	v_mfma_f32_16x16x32_bf16 v[142:145], v[150:153], v[22:25], v[162:165]
	v_sub_f32_e32 v130, v130, v129
	v_exp_f32_e32 v146, v130
	v_sub_f32_e32 v130, v131, v129
	v_exp_f32_e32 v148, v130
	v_sub_f32_e32 v130, v132, v129
	v_mfma_f32_16x16x32_bf16 v[142:145], v[158:161], v[18:21], v[142:145]
	v_exp_f32_e32 v150, v130
	v_sub_f32_e32 v130, v133, v129
	v_exp_f32_e32 v152, v130
	v_sub_f32_e32 v130, v134, v129
	v_sub_f32_e32 v125, v125, v129
	v_exp_f32_e32 v134, v130
	v_sub_f32_e32 v130, v135, v129
	v_exp_f32_e32 v154, v130
	v_sub_f32_e32 v130, v136, v129
	v_exp_f32_e32 v136, v125
	v_sub_f32_e32 v125, v137, v129
	v_exp_f32_e32 v158, v125
	v_maximum3_f32 v125, v138, v139, v140
	v_maximum3_f32 v133, v141, v142, v143
	v_maximum3_f32 v135, v144, v145, v145
	v_maximum3_f32 v125, v125, v133, v135
	v_mov_b32_e32 v133, v125
	s_nop 1
	v_permlane16_swap_b32_e32 v125, v133
	v_maximum3_f32 v125, v125, v133, v133
	v_mov_b32_e32 v133, v125
	s_nop 1
	v_permlane32_swap_b32_e32 v125, v133
	v_maximum3_f32 v160, v124, v125, v133
	v_sub_f32_e32 v125, v138, v160
	v_sub_f32_e32 v135, v140, v160
	v_sub_f32_e32 v138, v143, v160
	v_exp_f32_e32 v156, v130
	v_pk_mul_f32 v[56:57], v[56:57], v[136:137] op_sel_hi:[1,0]
	v_pk_mul_f32 v[54:55], v[54:55], v[136:137] op_sel_hi:[1,0]
	v_pk_mul_f32 v[64:65], v[64:65], v[136:137] op_sel_hi:[1,0]
	v_pk_mul_f32 v[62:63], v[62:63], v[136:137] op_sel_hi:[1,0]
	v_pk_mul_f32 v[60:61], v[60:61], v[136:137] op_sel_hi:[1,0]
	v_pk_mul_f32 v[58:59], v[58:59], v[136:137] op_sel_hi:[1,0]
	v_pk_mul_f32 v[52:53], v[52:53], v[136:137] op_sel_hi:[1,0]
	v_pk_mul_f32 v[50:51], v[50:51], v[136:137] op_sel_hi:[1,0]
	v_sub_f32_e32 v137, v124, v160
	v_exp_f32_e32 v151, v135
	v_sub_f32_e32 v135, v141, v160
	v_exp_f32_e32 v155, v138
	v_sub_f32_e32 v138, v144, v160
	v_exp_f32_e32 v147, v125
	v_sub_f32_e32 v125, v139, v160
	v_exp_f32_e32 v153, v135
	v_sub_f32_e32 v135, v142, v160
	v_exp_f32_e32 v157, v138
	v_sub_f32_e32 v138, v145, v160
	v_exp_f32_e32 v137, v137
	v_exp_f32_e32 v149, v125
	v_exp_f32_e32 v135, v135
	v_exp_f32_e32 v159, v138
	v_cvt_pk_bf16_f32 v130, v146, v148
	v_cvt_pk_bf16_f32 v131, v150, v152
	v_cvt_pk_bf16_f32 v132, v134, v154
	v_cvt_pk_bf16_f32 v133, v156, v158
	v_pk_add_f32 v[124:125], v[146:147], 0 op_sel_hi:[1,0]
	s_waitcnt lgkmcnt(12)
	v_mfma_f32_16x16x32_bf16 v[62:65], v[74:77], v[130:133], v[62:65]
	v_mov_b32_e32 v76, v137
	v_pk_add_f32 v[124:125], v[148:149], v[124:125]
	v_pk_mul_f32 v[48:49], v[48:49], v[76:77] op_sel_hi:[1,0]
	s_waitcnt lgkmcnt(10)
	v_mfma_f32_16x16x32_bf16 v[58:61], v[70:73], v[130:133], v[58:61]
	v_pk_mul_f32 v[46:47], v[46:47], v[76:77] op_sel_hi:[1,0]
	v_cvt_pk_bf16_f32 v70, v147, v149
	v_cvt_pk_bf16_f32 v71, v151, v153
	v_cvt_pk_bf16_f32 v72, v135, v155
	v_cvt_pk_bf16_f32 v73, v157, v159
	v_mfma_f32_16x16x32_bf16 v[54:57], v[78:81], v[130:133], v[54:57]
	v_pk_add_f32 v[78:79], v[150:151], v[124:125]
	v_pk_add_f32 v[78:79], v[152:153], v[78:79]
	s_waitcnt lgkmcnt(6)
	v_mfma_f32_16x16x32_bf16 v[46:49], v[14:17], v[70:73], v[46:49]
	v_pk_mul_f32 v[16:17], v[44:45], v[76:77] op_sel_hi:[1,0]
	v_pk_mul_f32 v[14:15], v[42:43], v[76:77] op_sel_hi:[1,0]
	v_pk_add_f32 v[74:75], v[134:135], v[78:79]
	v_mfma_f32_16x16x32_bf16 v[50:53], v[66:69], v[130:133], v[50:53]
	v_pk_add_f32 v[74:75], v[154:155], v[74:75]
	v_pk_add_f32 v[66:67], v[156:157], v[74:75]
	s_waitcnt lgkmcnt(4)
	v_mfma_f32_16x16x32_bf16 v[42:45], v[10:13], v[70:73], v[14:17]
	v_pk_mul_f32 v[12:13], v[40:41], v[76:77] op_sel_hi:[1,0]
	v_pk_mul_f32 v[10:11], v[38:39], v[76:77] op_sel_hi:[1,0]
	v_pk_add_f32 v[14:15], v[158:159], v[66:67]
	s_waitcnt lgkmcnt(2)
	v_mfma_f32_16x16x32_bf16 v[38:41], v[6:9], v[70:73], v[10:13]
	v_pk_mul_f32 v[8:9], v[36:37], v[76:77] op_sel_hi:[1,0]
	v_pk_mul_f32 v[6:7], v[34:35], v[76:77] op_sel_hi:[1,0]
	v_pk_fma_f32 v[98:99], v[98:99], v[136:137], v[14:15]
	s_waitcnt lgkmcnt(0)
	v_mfma_f32_16x16x32_bf16 v[34:37], v[2:5], v[70:73], v[6:9]
	v_mov_b32_e32 v125, v129
	v_mov_b32_e32 v124, v160
	s_branch .LBB0_300

; #define LAS __attribute__((address_space(3)))
; template <int MODE> ...
;     ...
;             if (MODE == 1) { const int ks = ktok0 + 64 * t + 32 * hf;
;                 if (ks + 31 < qtok0 - 128 || ks > qtok0 + 31 + 128) continue; }
;             bf16x8 kf[2][2][2];
; #pragma unroll
;             for (int jj = 0; jj < 2; ++jj)
; #pragma unroll
;                 for (int kt = 0; kt < 2; ++kt)
; #pragma unroll
;                     for (int ks = 0; ks < 2; ++ks) kf[jj][kt][ks] = *(const LAS bf16x8*)(Sl + kad[jj][ks] + (32 * hf + 16 * kt) * 128);
;             f32x4 bb[2][2];
; #pragma unroll
;             for (int jj = 0; jj < 2; ++jj) { const LAS f32x4* bl = bcp + ((MODE == 0) ? (dr0 + t - act0) * 8 : 16 * t + 8 * hf) + bofs[jj];
; #pragma unroll
;                 for (int kt = 0; kt < 2; ++kt) bb[jj][kt] = bl[4 * kt]; }
;             s16x4 vlo[2][4], vhi[2][4];
; #pragma unroll
;             for (int jj = 0; jj < 2; ++jj)
; #pragma unroll
;                 for (int dt = 0; dt < 4; ++dt) { const LAS unsigned char* vp = Sl + vad[jj] + (32 * hf) * 128 + ((dt ^ sv) << 5);
;                     vlo[jj][dt] = __builtin_bit_cast(s16x4, __builtin_amdgcn_ds_read_tr16_b64_v4i16((LAS s16x4*)(vp)));
;                     vhi[jj][dt] = __builtin_bit_cast(s16x4, __builtin_amdgcn_ds_read_tr16_b64_v4i16((LAS s16x4*)(vp + 2048))); }
;             __builtin_amdgcn_sched_barrier(0);
;             f32x4 s[2][2];
; #pragma unroll
;             for (int jj = 0; jj < 2; ++jj)
; #pragma unroll
;                 for (int kt = 0; kt < 2; ++kt) { f32x4 a = (MODE == 0) ? bb[jj][kt] + mneg[jj][kt] : bb[jj][kt];
;                     a = __builtin_amdgcn_mfma_f32_16x16x32_bf16(kf[jj][kt][0], qf[jj][0], a, 0, 0, 0);
;                     s[jj][kt] = __builtin_amdgcn_mfma_f32_16x16x32_bf16(kf[jj][kt][1], qf[jj][1], a, 0, 0, 0); }
;             u32x4 pw[2];
; #pragma unroll
;             for (int jj = 0; jj < 2; ++jj) {
;                 const float tm = vmax3(vmax3(s[jj][0][0], s[jj][0][1], s[jj][0][2]), vmax3(s[jj][0][3], s[jj][1][0], s[jj][1][1]), vmax3(s[jj][1][2], s[jj][1][3], s[jj][1][3]));
;                 const float mn = quad_max3(mrun[jj], tm);
;                 const float alpha = __builtin_amdgcn_exp2f(mrun[jj] - mn);
;                 mrun[jj] = mn;
;                 float rsum = 0.f;
; #pragma unroll
;                 for (int kt = 0; kt < 2; ++kt)
; #pragma unroll
.LBB0_345:
	s_add_i32 s0, s27, 32
	s_add_i32 s14, s27, 63
	s_cmp_lt_i32 s14, s41
	s_cselect_b64 s[50:51], -1, 0
	s_cmp_gt_i32 s0, s45
	s_cselect_b64 s[52:53], -1, 0
	s_or_b64 s[50:51], s[50:51], s[52:53]
	s_and_b64 vcc, exec, s[50:51]
	s_cbranch_vccnz .LBB0_333
	v_add_u32_e32 v2, 0x10080, v96
	v_add_u32_e32 v3, 0x100c0, v96
	ds_read_b128 v[100:103], v98 offset:4096
	ds_read_b128 v[104:107], v98 offset:6144
	ds_read_b128 v[108:111], v97 offset:4096
	ds_read_b128 v[112:115], v97 offset:6144
	ds_read_b128 v[96:99], v2
	ds_read_b128 v[118:121], v3
	v_add_u32_e32 v2, 0x10080, v85
	v_add_u32_e32 v3, 0x100c0, v85
	ds_read_b128 v[122:125], v2
	ds_read_b128 v[126:129], v3
	ds_read_b64_tr_b16 v[14:15], v84 offset:12288
	ds_read_b64_tr_b16 v[16:17], v84 offset:14336
	ds_read_b64_tr_b16 v[10:11], v83 offset:12288
	ds_read_b64_tr_b16 v[12:13], v83 offset:14336
	ds_read_b64_tr_b16 v[6:7], v81 offset:12288
	ds_read_b64_tr_b16 v[8:9], v81 offset:14336
	ds_read_b64_tr_b16 v[2:3], v0 offset:12288
	ds_read_b64_tr_b16 v[4:5], v0 offset:14336
	s_waitcnt lgkmcnt(11)
	v_mfma_f32_16x16x32_bf16 v[96:99], v[100:103], v[30:33], v[96:99]
	s_waitcnt lgkmcnt(10)
	v_mfma_f32_16x16x32_bf16 v[118:121], v[104:107], v[30:33], v[118:121]
	v_mfma_f32_16x16x32_bf16 v[96:99], v[108:111], v[26:29], v[96:99]
	v_mfma_f32_16x16x32_bf16 v[118:121], v[112:115], v[26:29], v[118:121]
	s_waitcnt lgkmcnt(9)
	v_mfma_f32_16x16x32_bf16 v[100:103], v[100:103], v[22:25], v[122:125]
	s_nop 4
	v_maximum3_f32 v0, v96, v97, v98
	v_maximum3_f32 v81, v99, v118, v119
	v_maximum3_f32 v83, v120, v121, v121
	v_maximum3_f32 v0, v0, v81, v83
	v_mov_b32_e32 v81, v0
	s_waitcnt lgkmcnt(8)
	v_mfma_f32_16x16x32_bf16 v[104:107], v[104:107], v[22:25], v[126:129]
	v_permlane16_swap_b32_e32 v0, v81
	v_maximum3_f32 v0, v0, v81, v81
	v_mov_b32_e32 v81, v0
	s_nop 1
	v_permlane32_swap_b32_e32 v0, v81
	v_mfma_f32_16x16x32_bf16 v[100:103], v[108:111], v[18:21], v[100:103]
	v_maximum3_f32 v81, v82, v0, v81
	v_sub_f32_e32 v0, v82, v81
	v_sub_f32_e32 v82, v96, v81
	v_mfma_f32_16x16x32_bf16 v[104:107], v[112:115], v[18:21], v[104:107]
	v_exp_f32_e32 v96, v82
	v_sub_f32_e32 v82, v97, v81
	v_exp_f32_e32 v108, v82
	v_sub_f32_e32 v82, v98, v81
	v_exp_f32_e32 v98, v82
	v_sub_f32_e32 v82, v99, v81
	v_exp_f32_e32 v122, v0
	v_maximum3_f32 v0, v100, v101, v102
	v_maximum3_f32 v97, v103, v104, v105
	v_maximum3_f32 v99, v106, v107, v107
	v_maximum3_f32 v0, v0, v97, v99
	v_mov_b32_e32 v97, v0
	s_nop 1
	v_permlane16_swap_b32_e32 v0, v97
	v_maximum3_f32 v0, v0, v97, v97
	v_mov_b32_e32 v97, v0
	s_nop 1
	v_permlane32_swap_b32_e32 v0, v97
	v_maximum3_f32 v117, v95, v0, v97
	v_sub_f32_e32 v0, v95, v117
	v_sub_f32_e32 v95, v100, v117
	v_exp_f32_e32 v97, v95
	v_sub_f32_e32 v95, v101, v117
	v_exp_f32_e32 v109, v95
	v_sub_f32_e32 v95, v102, v117
	v_exp_f32_e32 v99, v95
	v_sub_f32_e32 v95, v103, v117
	v_exp_f32_e32 v110, v82
	v_sub_f32_e32 v82, v118, v81
	v_exp_f32_e32 v111, v95
	v_sub_f32_e32 v95, v104, v117
	v_exp_f32_e32 v112, v82
	v_sub_f32_e32 v82, v119, v81
	v_exp_f32_e32 v113, v95
	v_sub_f32_e32 v95, v105, v117
	v_exp_f32_e32 v114, v82
	v_sub_f32_e32 v82, v120, v81
	v_exp_f32_e32 v115, v95
	v_sub_f32_e32 v95, v106, v117
	v_exp_f32_e32 v118, v82
	v_sub_f32_e32 v82, v121, v81
	v_pk_mul_f32 v[52:53], v[52:53], v[122:123] op_sel_hi:[1,0]
	v_pk_mul_f32 v[50:51], v[50:51], v[122:123] op_sel_hi:[1,0]
	v_pk_mul_f32 v[56:57], v[56:57], v[122:123] op_sel_hi:[1,0]
	v_pk_mul_f32 v[54:55], v[54:55], v[122:123] op_sel_hi:[1,0]
	v_pk_mul_f32 v[60:61], v[60:61], v[122:123] op_sel_hi:[1,0]
	v_pk_mul_f32 v[58:59], v[58:59], v[122:123] op_sel_hi:[1,0]
	v_pk_mul_f32 v[64:65], v[64:65], v[122:123] op_sel_hi:[1,0]
	v_pk_mul_f32 v[62:63], v[62:63], v[122:123] op_sel_hi:[1,0]
	v_exp_f32_e32 v119, v95
	v_sub_f32_e32 v95, v107, v117
	v_exp_f32_e32 v123, v0
	v_exp_f32_e32 v120, v82
	v_pk_add_f32 v[100:101], v[96:97], 0 op_sel_hi:[1,0]
	v_exp_f32_e32 v121, v95
	v_pk_add_f32 v[100:101], v[108:109], v[100:101]
	v_mov_b32_e32 v0, v123
	v_pk_add_f32 v[100:101], v[98:99], v[100:101]
	v_cvt_pk_bf16_f32 v82, v96, v108
	v_pk_add_f32 v[100:101], v[110:111], v[100:101]
	v_cvt_pk_bf16_f32 v83, v98, v110
	v_cvt_pk_bf16_f32 v84, v112, v114
	v_cvt_pk_bf16_f32 v85, v118, v120
	v_pk_add_f32 v[100:101], v[112:113], v[100:101]
	v_pk_mul_f32 v[36:37], v[36:37], v[0:1] op_sel_hi:[1,0]
	v_pk_mul_f32 v[34:35], v[34:35], v[0:1] op_sel_hi:[1,0]
	v_pk_mul_f32 v[40:41], v[40:41], v[0:1] op_sel_hi:[1,0]
	v_pk_mul_f32 v[38:39], v[38:39], v[0:1] op_sel_hi:[1,0]
	v_pk_mul_f32 v[44:45], v[44:45], v[0:1] op_sel_hi:[1,0]
	v_pk_mul_f32 v[42:43], v[42:43], v[0:1] op_sel_hi:[1,0]
	v_pk_mul_f32 v[48:49], v[48:49], v[0:1] op_sel_hi:[1,0]
	v_pk_mul_f32 v[46:47], v[46:47], v[0:1] op_sel_hi:[1,0]
	v_cvt_pk_bf16_f32 v96, v97, v109
	v_cvt_pk_bf16_f32 v97, v99, v111
	v_cvt_pk_bf16_f32 v98, v113, v115
	v_cvt_pk_bf16_f32 v99, v119, v121
	v_pk_add_f32 v[100:101], v[114:115], v[100:101]
	s_waitcnt lgkmcnt(6)
	v_mfma_f32_16x16x32_bf16 v[50:53], v[14:17], v[82:85], v[50:53]
	v_pk_add_f32 v[100:101], v[118:119], v[100:101]
	v_pk_add_f32 v[100:101], v[120:121], v[100:101]
	s_waitcnt lgkmcnt(4)
	v_mfma_f32_16x16x32_bf16 v[54:57], v[10:13], v[82:85], v[54:57]
	v_fma_f32 v88, v88, v122, v100
	v_fma_f32 v89, v89, v123, v101
	s_waitcnt lgkmcnt(2)
	v_mfma_f32_16x16x32_bf16 v[58:61], v[6:9], v[82:85], v[58:61]
	s_waitcnt lgkmcnt(0)
	v_mfma_f32_16x16x32_bf16 v[62:65], v[2:5], v[82:85], v[62:65]
	v_mfma_f32_16x16x32_bf16 v[34:37], v[14:17], v[96:99], v[34:37]
	v_mfma_f32_16x16x32_bf16 v[38:41], v[10:13], v[96:99], v[38:41]
	v_mfma_f32_16x16x32_bf16 v[42:45], v[6:9], v[96:99], v[42:45]
	v_mfma_f32_16x16x32_bf16 v[46:49], v[2:5], v[96:99], v[46:49]
	v_mov_b32_e32 v95, v117
	v_mov_b32_e32 v82, v81
	s_branch .LBB0_333

; #define LAS __attribute__((address_space(3)))
; template <int MODE> ...
;     ...
;             if (MODE == 1) { const int ks = ktok0 + 64 * t + 32 * hf;
;                 if (ks + 31 < qtok0 - 128 || ks > qtok0 + 31 + 128) continue; }
;             bf16x8 kf[2][2][2];
; #pragma unroll
;             for (int jj = 0; jj < 2; ++jj)
; #pragma unroll
;                 for (int kt = 0; kt < 2; ++kt)
; #pragma unroll
;                     for (int ks = 0; ks < 2; ++ks) kf[jj][kt][ks] = *(const LAS bf16x8*)(Sl + kad[jj][ks] + (32 * hf + 16 * kt) * 128);
;             f32x4 bb[2][2];
; #pragma unroll
;             for (int jj = 0; jj < 2; ++jj) { const LAS f32x4* bl = bcp + ((MODE == 0) ? (dr0 + t - act0) * 8 : 16 * t + 8 * hf) + bofs[jj];
; #pragma unroll
;                 for (int kt = 0; kt < 2; ++kt) bb[jj][kt] = bl[4 * kt]; }
;             s16x4 vlo[2][4], vhi[2][4];
; #pragma unroll
;             for (int jj = 0; jj < 2; ++jj)
; #pragma unroll
;                 for (int dt = 0; dt < 4; ++dt) { const LAS unsigned char* vp = Sl + vad[jj] + (32 * hf) * 128 + ((dt ^ sv) << 5);
;                     vlo[jj][dt] = __builtin_bit_cast(s16x4, __builtin_amdgcn_ds_read_tr16_b64_v4i16((LAS s16x4*)(vp)));
;                     vhi[jj][dt] = __builtin_bit_cast(s16x4, __builtin_amdgcn_ds_read_tr16_b64_v4i16((LAS s16x4*)(vp + 2048))); }
;             __builtin_amdgcn_sched_barrier(0);
;             f32x4 s[2][2];
; #pragma unroll
;             for (int jj = 0; jj < 2; ++jj)
; #pragma unroll
;                 for (int kt = 0; kt < 2; ++kt) { f32x4 a = (MODE == 0) ? bb[jj][kt] + mneg[jj][kt] : bb[jj][kt];
;                     a = __builtin_amdgcn_mfma_f32_16x16x32_bf16(kf[jj][kt][0], qf[jj][0], a, 0, 0, 0);
;                     s[jj][kt] = __builtin_amdgcn_mfma_f32_16x16x32_bf16(kf[jj][kt][1], qf[jj][1], a, 0, 0, 0); }
;             u32x4 pw[2];
; #pragma unroll
;             for (int jj = 0; jj < 2; ++jj) {
;                 const float tm = vmax3(vmax3(s[jj][0][0], s[jj][0][1], s[jj][0][2]), vmax3(s[jj][0][3], s[jj][1][0], s[jj][1][1]), vmax3(s[jj][1][2], s[jj][1][3], s[jj][1][3]));
;                 const float mn = quad_max3(mrun[jj], tm);
;                 const float alpha = __builtin_amdgcn_exp2f(mrun[jj] - mn);
;                 mrun[jj] = mn;
;                 float rsum = 0.f;
; #pragma unroll
;                 for (int kt = 0; kt < 2; ++kt)
; #pragma unroll
.LBB0_359:
	s_or_b32 s0, s30, 32
	s_add_i32 s0, s0, s24
	s_or_b32 s14, s0, 31
	s_cmp_lt_i32 s14, s31
	s_cselect_b64 s[30:31], -1, 0
	s_cmp_gt_i32 s0, s25
	s_cselect_b64 s[24:25], -1, 0
	s_or_b64 s[24:25], s[30:31], s[24:25]
	s_and_b64 vcc, exec, s[24:25]
	s_cbranch_vccnz .LBB0_361
	s_add_i32 s27, s27, s26
	v_lshl_add_u32 v83, v93, 4, s27
	ds_read_b128 v[66:69], v100 offset:4096
	ds_read_b128 v[70:73], v100 offset:6144
	ds_read_b128 v[74:77], v99 offset:4096
	ds_read_b128 v[78:81], v99 offset:6144
	ds_read_b128 v[100:103], v83 offset:128
	ds_read_b128 v[104:107], v83 offset:192
	v_lshl_add_u32 v83, v94, 4, s27
	ds_read_b128 v[108:111], v83 offset:128
	ds_read_b128 v[112:115], v83 offset:192
	ds_read_b64_tr_b16 v[118:119], v98 offset:12288
	ds_read_b64_tr_b16 v[120:121], v98 offset:14336
	ds_read_b64_tr_b16 v[122:123], v97 offset:12288
	ds_read_b64_tr_b16 v[124:125], v97 offset:14336
	ds_read_b64_tr_b16 v[126:127], v0 offset:12288
	ds_read_b64_tr_b16 v[128:129], v0 offset:14336
	ds_read_b64_tr_b16 v[130:131], v96 offset:12288
	ds_read_b64_tr_b16 v[132:133], v96 offset:14336
	s_waitcnt lgkmcnt(11)
	v_mfma_f32_16x16x32_bf16 v[96:99], v[66:69], v[30:33], v[100:103]
	s_waitcnt lgkmcnt(10)
	v_mfma_f32_16x16x32_bf16 v[30:33], v[70:73], v[30:33], v[104:107]
	v_mfma_f32_16x16x32_bf16 v[96:99], v[74:77], v[26:29], v[96:99]
	v_mfma_f32_16x16x32_bf16 v[26:29], v[78:81], v[26:29], v[30:33]
	s_nop 6
	v_maximum3_f32 v0, v96, v97, v98
	v_maximum3_f32 v30, v99, v26, v27
	v_maximum3_f32 v31, v28, v29, v29
	v_maximum3_f32 v0, v0, v30, v31
	v_mov_b32_e32 v30, v0
	s_nop 1
	v_permlane16_swap_b32_e32 v0, v30
	v_maximum3_f32 v0, v0, v30, v30
	v_mov_b32_e32 v30, v0
	s_nop 1
	v_permlane32_swap_b32_e32 v0, v30
	v_maximum3_f32 v0, v82, v0, v30
	s_waitcnt lgkmcnt(9)
	v_mfma_f32_16x16x32_bf16 v[30:33], v[66:69], v[22:25], v[108:111]
	v_sub_f32_e32 v83, v82, v0
	v_sub_f32_e32 v66, v97, v0
	v_exp_f32_e32 v84, v66
	s_waitcnt lgkmcnt(8)
	v_mfma_f32_16x16x32_bf16 v[22:25], v[70:73], v[22:25], v[112:115]
	v_sub_f32_e32 v66, v98, v0
	v_sub_f32_e32 v82, v96, v0
	v_sub_f32_e32 v26, v26, v0
	v_mfma_f32_16x16x32_bf16 v[30:33], v[74:77], v[18:21], v[30:33]
	v_exp_f32_e32 v74, v66
	v_sub_f32_e32 v66, v99, v0
	v_exp_f32_e32 v82, v82
	v_mfma_f32_16x16x32_bf16 v[18:21], v[78:81], v[18:21], v[22:25]
	v_exp_f32_e32 v78, v83
	v_exp_f32_e32 v70, v66
	v_exp_f32_e32 v72, v26
	v_sub_f32_e32 v22, v27, v0
	v_exp_f32_e32 v76, v22
	v_sub_f32_e32 v22, v28, v0
	v_sub_f32_e32 v0, v29, v0
	v_exp_f32_e32 v80, v22
	v_exp_f32_e32 v94, v0
	v_pk_mul_f32 v[22:23], v[50:51], v[78:79] op_sel_hi:[1,0]
	v_maximum3_f32 v0, v30, v31, v32
	v_maximum3_f32 v50, v33, v18, v19
	v_maximum3_f32 v51, v20, v21, v21
	v_maximum3_f32 v0, v0, v50, v51
	v_mov_b32_e32 v50, v0
	s_nop 1
	v_permlane16_swap_b32_e32 v0, v50
	v_maximum3_f32 v0, v0, v50, v50
	v_mov_b32_e32 v50, v0
	s_nop 1
	v_permlane32_swap_b32_e32 v0, v50
	v_maximum3_f32 v0, v95, v0, v50
	v_sub_f32_e32 v30, v30, v0
	v_exp_f32_e32 v83, v30
	v_sub_f32_e32 v30, v31, v0
	v_exp_f32_e32 v85, v30
	v_sub_f32_e32 v30, v32, v0
	v_sub_f32_e32 v18, v18, v0
	v_exp_f32_e32 v75, v30
	v_sub_f32_e32 v30, v33, v0
	v_exp_f32_e32 v73, v18
	v_sub_f32_e32 v18, v19, v0
	v_sub_f32_e32 v50, v95, v0
	v_exp_f32_e32 v71, v30
	v_exp_f32_e32 v77, v18
	v_sub_f32_e32 v18, v20, v0
	v_pk_mul_f32 v[24:25], v[52:53], v[78:79] op_sel_hi:[1,0]
	v_pk_mul_f32 v[28:29], v[56:57], v[78:79] op_sel_hi:[1,0]
	v_pk_mul_f32 v[26:27], v[54:55], v[78:79] op_sel_hi:[1,0]
	v_pk_mul_f32 v[60:61], v[60:61], v[78:79] op_sel_hi:[1,0]
	v_pk_mul_f32 v[58:59], v[58:59], v[78:79] op_sel_hi:[1,0]
	v_pk_mul_f32 v[64:65], v[64:65], v[78:79] op_sel_hi:[1,0]
	v_pk_mul_f32 v[62:63], v[62:63], v[78:79] op_sel_hi:[1,0]
	v_exp_f32_e32 v81, v18
	v_sub_f32_e32 v0, v21, v0
	v_exp_f32_e32 v79, v50
	v_pk_add_f32 v[18:19], v[82:83], 0 op_sel_hi:[1,0]
	v_exp_f32_e32 v95, v0
	v_pk_add_f32 v[18:19], v[84:85], v[18:19]
	v_cvt_pk_bf16_f32 v66, v82, v84
	v_pk_add_f32 v[18:19], v[74:75], v[18:19]
	v_cvt_pk_bf16_f32 v67, v74, v70
	v_pk_add_f32 v[18:19], v[70:71], v[18:19]
	v_cvt_pk_bf16_f32 v68, v72, v76
	v_cvt_pk_bf16_f32 v69, v80, v94
	v_pk_add_f32 v[18:19], v[72:73], v[18:19]
	v_mov_b32_e32 v0, v79
	s_waitcnt lgkmcnt(6)
	v_mfma_f32_16x16x32_bf16 v[50:53], v[118:121], v[66:69], v[22:25]
	v_pk_mul_f32 v[20:21], v[36:37], v[0:1] op_sel_hi:[1,0]
	s_waitcnt lgkmcnt(4)
	v_mfma_f32_16x16x32_bf16 v[54:57], v[122:125], v[66:69], v[26:29]
	v_cvt_pk_bf16_f32 v22, v83, v85
	v_cvt_pk_bf16_f32 v23, v75, v71
	v_cvt_pk_bf16_f32 v24, v73, v77
	v_pk_add_f32 v[26:27], v[76:77], v[18:19]
	v_pk_mul_f32 v[18:19], v[34:35], v[0:1] op_sel_hi:[1,0]
	v_cvt_pk_bf16_f32 v25, v81, v95
	s_waitcnt lgkmcnt(2)
	v_mfma_f32_16x16x32_bf16 v[58:61], v[126:129], v[66:69], v[58:61]
	v_pk_add_f32 v[26:27], v[80:81], v[26:27]
	v_pk_add_f32 v[26:27], v[94:95], v[26:27]
	v_mfma_f32_16x16x32_bf16 v[34:37], v[118:121], v[22:25], v[18:21]
	v_fma_f32 v88, v88, v78, v26
	v_fma_f32 v89, v89, v79, v27
	s_nop 0
	v_pk_mul_f32 v[20:21], v[40:41], v[0:1] op_sel_hi:[1,0]
	v_pk_mul_f32 v[18:19], v[38:39], v[0:1] op_sel_hi:[1,0]
	s_waitcnt lgkmcnt(0)
	v_mfma_f32_16x16x32_bf16 v[62:65], v[130:133], v[66:69], v[62:65]
	v_mfma_f32_16x16x32_bf16 v[38:41], v[122:125], v[22:25], v[18:21]
	s_nop 2
	v_pk_mul_f32 v[20:21], v[44:45], v[0:1] op_sel_hi:[1,0]
	v_pk_mul_f32 v[18:19], v[42:43], v[0:1] op_sel_hi:[1,0]
	s_nop 1
	v_mfma_f32_16x16x32_bf16 v[42:45], v[126:129], v[22:25], v[18:21]
	s_nop 2
	v_pk_mul_f32 v[20:21], v[48:49], v[0:1] op_sel_hi:[1,0]
	v_pk_mul_f32 v[18:19], v[46:47], v[0:1] op_sel_hi:[1,0]
	s_nop 1
	v_mfma_f32_16x16x32_bf16 v[46:49], v[130:133], v[22:25], v[18:21]
